# EpiSwiglu epilogue (FFN-up): same per-element arithmetic done with packed f32 multiplies/adds on the accumulator register pairs, no register shuffling, all 8 row-stat loads up front
# speedup vs baseline: 1.0144x; 1.0144x over previous
.LBB0_1134:
	v_lshl_add_u32 v130, s0, 8, v148
	v_ashrrev_i32_e32 v131, 31, v130
	v_lshl_add_u64 v[190:191], v[130:131], 4, s[8:9]
	global_load_dwordx4 v[222:225], v[190:191], off
	global_load_dwordx4 v[226:229], v[190:191], off offset:256
	global_load_dwordx4 v[230:233], v[190:191], off offset:512
	global_load_dwordx4 v[234:237], v[190:191], off offset:768
	global_load_dwordx4 v[238:241], v[190:191], off offset:2048
	global_load_dwordx4 v[242:245], v[190:191], off offset:2304
	global_load_dwordx4 v[198:201], v[190:191], off offset:2560
	global_load_dwordx4 v[202:205], v[190:191], off offset:2816
	s_lshl_b32 s1, s1, 1
	s_or_b32 s1, s1, s36
	s_mul_hi_i32 s2, s0, 44
	s_mul_i32 s0, s0, 44
	s_ashr_i32 s3, s1, 31
	s_add_u32 s0, s0, s1
	s_addc_u32 s1, s2, s3
	s_lshl_b64 s[0:1], s[0:1], 15
	v_lshl_add_u64 v[178:179], v[166:167], 0, s[0:1]
	v_lshl_add_u64 v[178:179], v[178:179], 0, v[150:151]
	s_mov_b64 s[2:3], 0x1000
	v_lshl_add_u64 v[180:181], v[178:179], 0, s[2:3]
	s_mov_b64 s[2:3], 0x5000
	v_lshl_add_u64 v[182:183], v[178:179], 0, s[2:3]
	s_mov_b32 s2, 0xbfb8aa3b
	s_mov_b32 s3, 0xbfb8aa3b
	s_mov_b32 s100, 1.0
	s_mov_b32 s101, 1.0
	s_waitcnt vmcnt(7)
	v_add_f32_e32 v140, v222, v223
	v_add_f32_e32 v141, v224, v225
	v_add_f32_e32 v140, v140, v141
	v_fmamk_f32 v140, v140, 0x3a800000, v207
	v_rsq_f32_e32 v184, v140
	s_nop 0
	v_pk_mul_f32 v[118:119], v[118:119], v[184:185] op_sel_hi:[1,0]
	v_pk_mul_f32 v[120:121], v[120:121], v[184:185] op_sel_hi:[1,0]
	v_pk_mul_f32 v[114:115], v[114:115], v[184:185] op_sel_hi:[1,0]
	v_pk_mul_f32 v[116:117], v[116:117], v[184:185] op_sel_hi:[1,0]
	v_pk_mul_f32 v[126:127], v[126:127], v[184:185] op_sel_hi:[1,0]
	v_pk_mul_f32 v[128:129], v[128:129], v[184:185] op_sel_hi:[1,0]
	v_pk_mul_f32 v[122:123], v[122:123], v[184:185] op_sel_hi:[1,0]
	v_pk_mul_f32 v[124:125], v[124:125], v[184:185] op_sel_hi:[1,0]
	v_pk_mul_f32 v[132:133], v[118:119], s[2:3]
	v_pk_mul_f32 v[134:135], v[120:121], s[2:3]
	v_pk_mul_f32 v[136:137], v[114:115], s[2:3]
	v_pk_mul_f32 v[138:139], v[116:117], s[2:3]
	v_exp_f32_e32 v132, v132
	v_exp_f32_e32 v133, v133
	v_exp_f32_e32 v134, v134
	v_exp_f32_e32 v135, v135
	v_exp_f32_e32 v136, v136
	v_exp_f32_e32 v137, v137
	v_exp_f32_e32 v138, v138
	v_exp_f32_e32 v139, v139
	v_pk_add_f32 v[132:133], v[132:133], s[100:101]
	v_pk_add_f32 v[134:135], v[134:135], s[100:101]
	v_pk_add_f32 v[136:137], v[136:137], s[100:101]
	v_pk_add_f32 v[138:139], v[138:139], s[100:101]
	v_rcp_f32_e32 v132, v132
	v_rcp_f32_e32 v133, v133
	v_rcp_f32_e32 v134, v134
	v_rcp_f32_e32 v135, v135
	v_rcp_f32_e32 v136, v136
	v_rcp_f32_e32 v137, v137
	v_rcp_f32_e32 v138, v138
	v_rcp_f32_e32 v139, v139
	v_pk_mul_f32 v[118:119], v[118:119], v[132:133]
	v_pk_mul_f32 v[120:121], v[120:121], v[134:135]
	v_pk_mul_f32 v[114:115], v[114:115], v[136:137]
	v_pk_mul_f32 v[116:117], v[116:117], v[138:139]
	v_pk_mul_f32 v[118:119], v[118:119], v[126:127]
	v_pk_mul_f32 v[120:121], v[120:121], v[128:129]
	v_pk_mul_f32 v[114:115], v[114:115], v[122:123]
	v_pk_mul_f32 v[116:117], v[116:117], v[124:125]
	v_cvt_pk_bf16_f32 v192, v118, v119
	v_cvt_pk_bf16_f32 v193, v120, v121
	v_cvt_pk_bf16_f32 v194, v114, v115
	v_cvt_pk_bf16_f32 v195, v116, v117
	global_store_dwordx4 v[180:181], v[192:195], off offset:-4096
	s_waitcnt vmcnt(7)
	v_add_f32_e32 v140, v226, v227
	v_add_f32_e32 v141, v228, v229
	v_add_f32_e32 v140, v140, v141
	v_fmamk_f32 v140, v140, 0x3a800000, v207
	v_rsq_f32_e32 v184, v140
	s_nop 0
	v_pk_mul_f32 v[110:111], v[110:111], v[184:185] op_sel_hi:[1,0]
	v_pk_mul_f32 v[112:113], v[112:113], v[184:185] op_sel_hi:[1,0]
	v_pk_mul_f32 v[102:103], v[102:103], v[184:185] op_sel_hi:[1,0]
	v_pk_mul_f32 v[104:105], v[104:105], v[184:185] op_sel_hi:[1,0]
	v_pk_mul_f32 v[106:107], v[106:107], v[184:185] op_sel_hi:[1,0]
	v_pk_mul_f32 v[108:109], v[108:109], v[184:185] op_sel_hi:[1,0]
	v_pk_mul_f32 v[98:99], v[98:99], v[184:185] op_sel_hi:[1,0]
	v_pk_mul_f32 v[100:101], v[100:101], v[184:185] op_sel_hi:[1,0]
	v_pk_mul_f32 v[132:133], v[110:111], s[2:3]
	v_pk_mul_f32 v[134:135], v[112:113], s[2:3]
	v_pk_mul_f32 v[136:137], v[102:103], s[2:3]
	v_pk_mul_f32 v[138:139], v[104:105], s[2:3]
	v_exp_f32_e32 v132, v132
	v_exp_f32_e32 v133, v133
	v_exp_f32_e32 v134, v134
	v_exp_f32_e32 v135, v135
	v_exp_f32_e32 v136, v136
	v_exp_f32_e32 v137, v137
	v_exp_f32_e32 v138, v138
	v_exp_f32_e32 v139, v139
	v_pk_add_f32 v[132:133], v[132:133], s[100:101]
	v_pk_add_f32 v[134:135], v[134:135], s[100:101]
	v_pk_add_f32 v[136:137], v[136:137], s[100:101]
	v_pk_add_f32 v[138:139], v[138:139], s[100:101]
	v_rcp_f32_e32 v132, v132
	v_rcp_f32_e32 v133, v133
	v_rcp_f32_e32 v134, v134
	v_rcp_f32_e32 v135, v135
	v_rcp_f32_e32 v136, v136
	v_rcp_f32_e32 v137, v137
	v_rcp_f32_e32 v138, v138
	v_rcp_f32_e32 v139, v139
	v_pk_mul_f32 v[110:111], v[110:111], v[132:133]
	v_pk_mul_f32 v[112:113], v[112:113], v[134:135]
	v_pk_mul_f32 v[102:103], v[102:103], v[136:137]
	v_pk_mul_f32 v[104:105], v[104:105], v[138:139]
	v_pk_mul_f32 v[110:111], v[110:111], v[106:107]
	v_pk_mul_f32 v[112:113], v[112:113], v[108:109]
	v_pk_mul_f32 v[102:103], v[102:103], v[98:99]
	v_pk_mul_f32 v[104:105], v[104:105], v[100:101]
	v_cvt_pk_bf16_f32 v186, v110, v111
	v_cvt_pk_bf16_f32 v187, v112, v113
	v_cvt_pk_bf16_f32 v188, v102, v103
	v_cvt_pk_bf16_f32 v189, v104, v105
	global_store_dwordx4 v[180:181], v[186:189], off offset:-2048
	s_waitcnt vmcnt(7)
	v_add_f32_e32 v140, v230, v231
	v_add_f32_e32 v141, v232, v233
	v_add_f32_e32 v140, v140, v141
	v_fmamk_f32 v140, v140, 0x3a800000, v207
	v_rsq_f32_e32 v184, v140
	s_nop 0
	v_pk_mul_f32 v[92:93], v[92:93], v[184:185] op_sel_hi:[1,0]
	v_pk_mul_f32 v[94:95], v[94:95], v[184:185] op_sel_hi:[1,0]
	v_pk_mul_f32 v[84:85], v[84:85], v[184:185] op_sel_hi:[1,0]
	v_pk_mul_f32 v[86:87], v[86:87], v[184:185] op_sel_hi:[1,0]
	v_pk_mul_f32 v[88:89], v[88:89], v[184:185] op_sel_hi:[1,0]
	v_pk_mul_f32 v[90:91], v[90:91], v[184:185] op_sel_hi:[1,0]
	v_pk_mul_f32 v[80:81], v[80:81], v[184:185] op_sel_hi:[1,0]
	v_pk_mul_f32 v[82:83], v[82:83], v[184:185] op_sel_hi:[1,0]
	v_pk_mul_f32 v[132:133], v[92:93], s[2:3]
	v_pk_mul_f32 v[134:135], v[94:95], s[2:3]
	v_pk_mul_f32 v[136:137], v[84:85], s[2:3]
	v_pk_mul_f32 v[138:139], v[86:87], s[2:3]
	v_exp_f32_e32 v132, v132
	v_exp_f32_e32 v133, v133
	v_exp_f32_e32 v134, v134
	v_exp_f32_e32 v135, v135
	v_exp_f32_e32 v136, v136
	v_exp_f32_e32 v137, v137
	v_exp_f32_e32 v138, v138
	v_exp_f32_e32 v139, v139
	v_pk_add_f32 v[132:133], v[132:133], s[100:101]
	v_pk_add_f32 v[134:135], v[134:135], s[100:101]
	v_pk_add_f32 v[136:137], v[136:137], s[100:101]
	v_pk_add_f32 v[138:139], v[138:139], s[100:101]
	v_rcp_f32_e32 v132, v132
	v_rcp_f32_e32 v133, v133
	v_rcp_f32_e32 v134, v134
	v_rcp_f32_e32 v135, v135
	v_rcp_f32_e32 v136, v136
	v_rcp_f32_e32 v137, v137
	v_rcp_f32_e32 v138, v138
	v_rcp_f32_e32 v139, v139
	v_pk_mul_f32 v[92:93], v[92:93], v[132:133]
	v_pk_mul_f32 v[94:95], v[94:95], v[134:135]
	v_pk_mul_f32 v[84:85], v[84:85], v[136:137]
	v_pk_mul_f32 v[86:87], v[86:87], v[138:139]
	v_pk_mul_f32 v[92:93], v[92:93], v[88:89]
	v_pk_mul_f32 v[94:95], v[94:95], v[90:91]
	v_pk_mul_f32 v[84:85], v[84:85], v[80:81]
	v_pk_mul_f32 v[86:87], v[86:87], v[82:83]
	v_cvt_pk_bf16_f32 v192, v92, v93
	v_cvt_pk_bf16_f32 v193, v94, v95
	v_cvt_pk_bf16_f32 v194, v84, v85
	v_cvt_pk_bf16_f32 v195, v86, v87
	global_store_dwordx4 v[180:181], v[192:195], off
	s_waitcnt vmcnt(7)
	v_add_f32_e32 v140, v234, v235
	v_add_f32_e32 v141, v236, v237
	v_add_f32_e32 v140, v140, v141
	v_fmamk_f32 v140, v140, 0x3a800000, v207
	v_rsq_f32_e32 v184, v140
	s_nop 0
	v_pk_mul_f32 v[76:77], v[76:77], v[184:185] op_sel_hi:[1,0]
	v_pk_mul_f32 v[78:79], v[78:79], v[184:185] op_sel_hi:[1,0]
	v_pk_mul_f32 v[68:69], v[68:69], v[184:185] op_sel_hi:[1,0]
	v_pk_mul_f32 v[70:71], v[70:71], v[184:185] op_sel_hi:[1,0]
	v_pk_mul_f32 v[72:73], v[72:73], v[184:185] op_sel_hi:[1,0]
	v_pk_mul_f32 v[74:75], v[74:75], v[184:185] op_sel_hi:[1,0]
	v_pk_mul_f32 v[64:65], v[64:65], v[184:185] op_sel_hi:[1,0]
	v_pk_mul_f32 v[66:67], v[66:67], v[184:185] op_sel_hi:[1,0]
	v_pk_mul_f32 v[132:133], v[76:77], s[2:3]
	v_pk_mul_f32 v[134:135], v[78:79], s[2:3]
	v_pk_mul_f32 v[136:137], v[68:69], s[2:3]
	v_pk_mul_f32 v[138:139], v[70:71], s[2:3]
	v_exp_f32_e32 v132, v132
	v_exp_f32_e32 v133, v133
	v_exp_f32_e32 v134, v134
	v_exp_f32_e32 v135, v135
	v_exp_f32_e32 v136, v136
	v_exp_f32_e32 v137, v137
	v_exp_f32_e32 v138, v138
	v_exp_f32_e32 v139, v139
	v_pk_add_f32 v[132:133], v[132:133], s[100:101]
	v_pk_add_f32 v[134:135], v[134:135], s[100:101]
	v_pk_add_f32 v[136:137], v[136:137], s[100:101]
	v_pk_add_f32 v[138:139], v[138:139], s[100:101]
	v_rcp_f32_e32 v132, v132
	v_rcp_f32_e32 v133, v133
	v_rcp_f32_e32 v134, v134
	v_rcp_f32_e32 v135, v135
	v_rcp_f32_e32 v136, v136
	v_rcp_f32_e32 v137, v137
	v_rcp_f32_e32 v138, v138
	v_rcp_f32_e32 v139, v139
	v_pk_mul_f32 v[76:77], v[76:77], v[132:133]
	v_pk_mul_f32 v[78:79], v[78:79], v[134:135]
	v_pk_mul_f32 v[68:69], v[68:69], v[136:137]
	v_pk_mul_f32 v[70:71], v[70:71], v[138:139]
	v_pk_mul_f32 v[76:77], v[76:77], v[72:73]
	v_pk_mul_f32 v[78:79], v[78:79], v[74:75]
	v_pk_mul_f32 v[68:69], v[68:69], v[64:65]
	v_pk_mul_f32 v[70:71], v[70:71], v[66:67]
	v_cvt_pk_bf16_f32 v186, v76, v77
	v_cvt_pk_bf16_f32 v187, v78, v79
	v_cvt_pk_bf16_f32 v188, v68, v69
	v_cvt_pk_bf16_f32 v189, v70, v71
	global_store_dwordx4 v[180:181], v[186:189], off offset:2048
	s_waitcnt vmcnt(7)
	v_add_f32_e32 v140, v238, v239
	v_add_f32_e32 v141, v240, v241
	v_add_f32_e32 v140, v140, v141
	v_fmamk_f32 v140, v140, 0x3a800000, v207
	v_rsq_f32_e32 v184, v140
	s_nop 0
	v_pk_mul_f32 v[60:61], v[60:61], v[184:185] op_sel_hi:[1,0]
	v_pk_mul_f32 v[62:63], v[62:63], v[184:185] op_sel_hi:[1,0]
	v_pk_mul_f32 v[52:53], v[52:53], v[184:185] op_sel_hi:[1,0]
	v_pk_mul_f32 v[54:55], v[54:55], v[184:185] op_sel_hi:[1,0]
	v_pk_mul_f32 v[56:57], v[56:57], v[184:185] op_sel_hi:[1,0]
	v_pk_mul_f32 v[58:59], v[58:59], v[184:185] op_sel_hi:[1,0]
	v_pk_mul_f32 v[48:49], v[48:49], v[184:185] op_sel_hi:[1,0]
	v_pk_mul_f32 v[50:51], v[50:51], v[184:185] op_sel_hi:[1,0]
	v_pk_mul_f32 v[132:133], v[60:61], s[2:3]
	v_pk_mul_f32 v[134:135], v[62:63], s[2:3]
	v_pk_mul_f32 v[136:137], v[52:53], s[2:3]
	v_pk_mul_f32 v[138:139], v[54:55], s[2:3]
	v_exp_f32_e32 v132, v132
	v_exp_f32_e32 v133, v133
	v_exp_f32_e32 v134, v134
	v_exp_f32_e32 v135, v135
	v_exp_f32_e32 v136, v136
	v_exp_f32_e32 v137, v137
	v_exp_f32_e32 v138, v138
	v_exp_f32_e32 v139, v139
	v_pk_add_f32 v[132:133], v[132:133], s[100:101]
	v_pk_add_f32 v[134:135], v[134:135], s[100:101]
	v_pk_add_f32 v[136:137], v[136:137], s[100:101]
	v_pk_add_f32 v[138:139], v[138:139], s[100:101]
	v_rcp_f32_e32 v132, v132
	v_rcp_f32_e32 v133, v133
	v_rcp_f32_e32 v134, v134
	v_rcp_f32_e32 v135, v135
	v_rcp_f32_e32 v136, v136
	v_rcp_f32_e32 v137, v137
	v_rcp_f32_e32 v138, v138
	v_rcp_f32_e32 v139, v139
	v_pk_mul_f32 v[60:61], v[60:61], v[132:133]
	v_pk_mul_f32 v[62:63], v[62:63], v[134:135]
	v_pk_mul_f32 v[52:53], v[52:53], v[136:137]
	v_pk_mul_f32 v[54:55], v[54:55], v[138:139]
	v_pk_mul_f32 v[60:61], v[60:61], v[56:57]
	v_pk_mul_f32 v[62:63], v[62:63], v[58:59]
	v_pk_mul_f32 v[52:53], v[52:53], v[48:49]
	v_pk_mul_f32 v[54:55], v[54:55], v[50:51]
	v_cvt_pk_bf16_f32 v192, v60, v61
	v_cvt_pk_bf16_f32 v193, v62, v63
	v_cvt_pk_bf16_f32 v194, v52, v53
	v_cvt_pk_bf16_f32 v195, v54, v55
	global_store_dwordx4 v[182:183], v[192:195], off offset:-4096
	s_waitcnt vmcnt(7)
	v_add_f32_e32 v140, v242, v243
	v_add_f32_e32 v141, v244, v245
	v_add_f32_e32 v140, v140, v141
	v_fmamk_f32 v140, v140, 0x3a800000, v207
	v_rsq_f32_e32 v184, v140
	s_nop 0
	v_pk_mul_f32 v[44:45], v[44:45], v[184:185] op_sel_hi:[1,0]
	v_pk_mul_f32 v[46:47], v[46:47], v[184:185] op_sel_hi:[1,0]
	v_pk_mul_f32 v[36:37], v[36:37], v[184:185] op_sel_hi:[1,0]
	v_pk_mul_f32 v[38:39], v[38:39], v[184:185] op_sel_hi:[1,0]
	v_pk_mul_f32 v[40:41], v[40:41], v[184:185] op_sel_hi:[1,0]
	v_pk_mul_f32 v[42:43], v[42:43], v[184:185] op_sel_hi:[1,0]
	v_pk_mul_f32 v[32:33], v[32:33], v[184:185] op_sel_hi:[1,0]
	v_pk_mul_f32 v[34:35], v[34:35], v[184:185] op_sel_hi:[1,0]
	v_pk_mul_f32 v[132:133], v[44:45], s[2:3]
	v_pk_mul_f32 v[134:135], v[46:47], s[2:3]
	v_pk_mul_f32 v[136:137], v[36:37], s[2:3]
	v_pk_mul_f32 v[138:139], v[38:39], s[2:3]
	v_exp_f32_e32 v132, v132
	v_exp_f32_e32 v133, v133
	v_exp_f32_e32 v134, v134
	v_exp_f32_e32 v135, v135
	v_exp_f32_e32 v136, v136
	v_exp_f32_e32 v137, v137
	v_exp_f32_e32 v138, v138
	v_exp_f32_e32 v139, v139
	v_pk_add_f32 v[132:133], v[132:133], s[100:101]
	v_pk_add_f32 v[134:135], v[134:135], s[100:101]
	v_pk_add_f32 v[136:137], v[136:137], s[100:101]
	v_pk_add_f32 v[138:139], v[138:139], s[100:101]
	v_rcp_f32_e32 v132, v132
	v_rcp_f32_e32 v133, v133
	v_rcp_f32_e32 v134, v134
	v_rcp_f32_e32 v135, v135
	v_rcp_f32_e32 v136, v136
	v_rcp_f32_e32 v137, v137
	v_rcp_f32_e32 v138, v138
	v_rcp_f32_e32 v139, v139
	v_pk_mul_f32 v[44:45], v[44:45], v[132:133]
	v_pk_mul_f32 v[46:47], v[46:47], v[134:135]
	v_pk_mul_f32 v[36:37], v[36:37], v[136:137]
	v_pk_mul_f32 v[38:39], v[38:39], v[138:139]
	v_pk_mul_f32 v[44:45], v[44:45], v[40:41]
	v_pk_mul_f32 v[46:47], v[46:47], v[42:43]
	v_pk_mul_f32 v[36:37], v[36:37], v[32:33]
	v_pk_mul_f32 v[38:39], v[38:39], v[34:35]
	v_cvt_pk_bf16_f32 v186, v44, v45
	v_cvt_pk_bf16_f32 v187, v46, v47
	v_cvt_pk_bf16_f32 v188, v36, v37
	v_cvt_pk_bf16_f32 v189, v38, v39
	global_store_dwordx4 v[182:183], v[186:189], off offset:-2048
	s_waitcnt vmcnt(7)
	v_add_f32_e32 v140, v198, v199
	v_add_f32_e32 v141, v200, v201
	v_add_f32_e32 v140, v140, v141
	v_fmamk_f32 v140, v140, 0x3a800000, v207
	v_rsq_f32_e32 v184, v140
	s_nop 0
	v_pk_mul_f32 v[28:29], v[28:29], v[184:185] op_sel_hi:[1,0]
	v_pk_mul_f32 v[30:31], v[30:31], v[184:185] op_sel_hi:[1,0]
	v_pk_mul_f32 v[20:21], v[20:21], v[184:185] op_sel_hi:[1,0]
	v_pk_mul_f32 v[22:23], v[22:23], v[184:185] op_sel_hi:[1,0]
	v_pk_mul_f32 v[24:25], v[24:25], v[184:185] op_sel_hi:[1,0]
	v_pk_mul_f32 v[26:27], v[26:27], v[184:185] op_sel_hi:[1,0]
	v_pk_mul_f32 v[16:17], v[16:17], v[184:185] op_sel_hi:[1,0]
	v_pk_mul_f32 v[18:19], v[18:19], v[184:185] op_sel_hi:[1,0]
	v_pk_mul_f32 v[132:133], v[28:29], s[2:3]
	v_pk_mul_f32 v[134:135], v[30:31], s[2:3]
	v_pk_mul_f32 v[136:137], v[20:21], s[2:3]
	v_pk_mul_f32 v[138:139], v[22:23], s[2:3]
	v_exp_f32_e32 v132, v132
	v_exp_f32_e32 v133, v133
	v_exp_f32_e32 v134, v134
	v_exp_f32_e32 v135, v135
	v_exp_f32_e32 v136, v136
	v_exp_f32_e32 v137, v137
	v_exp_f32_e32 v138, v138
	v_exp_f32_e32 v139, v139
	v_pk_add_f32 v[132:133], v[132:133], s[100:101]
	v_pk_add_f32 v[134:135], v[134:135], s[100:101]
	v_pk_add_f32 v[136:137], v[136:137], s[100:101]
	v_pk_add_f32 v[138:139], v[138:139], s[100:101]
	v_rcp_f32_e32 v132, v132
	v_rcp_f32_e32 v133, v133
	v_rcp_f32_e32 v134, v134
	v_rcp_f32_e32 v135, v135
	v_rcp_f32_e32 v136, v136
	v_rcp_f32_e32 v137, v137
	v_rcp_f32_e32 v138, v138
	v_rcp_f32_e32 v139, v139
	v_pk_mul_f32 v[28:29], v[28:29], v[132:133]
	v_pk_mul_f32 v[30:31], v[30:31], v[134:135]
	v_pk_mul_f32 v[20:21], v[20:21], v[136:137]
	v_pk_mul_f32 v[22:23], v[22:23], v[138:139]
	v_pk_mul_f32 v[28:29], v[28:29], v[24:25]
	v_pk_mul_f32 v[30:31], v[30:31], v[26:27]
	v_pk_mul_f32 v[20:21], v[20:21], v[16:17]
	v_pk_mul_f32 v[22:23], v[22:23], v[18:19]
	v_cvt_pk_bf16_f32 v192, v28, v29
	v_cvt_pk_bf16_f32 v193, v30, v31
	v_cvt_pk_bf16_f32 v194, v20, v21
	v_cvt_pk_bf16_f32 v195, v22, v23
	global_store_dwordx4 v[182:183], v[192:195], off
	s_waitcnt vmcnt(7)
	v_add_f32_e32 v140, v202, v203
	v_add_f32_e32 v141, v204, v205
	v_add_f32_e32 v140, v140, v141
	v_fmamk_f32 v140, v140, 0x3a800000, v207
	v_rsq_f32_e32 v184, v140
	s_nop 0
	v_pk_mul_f32 v[12:13], v[12:13], v[184:185] op_sel_hi:[1,0]
	v_pk_mul_f32 v[14:15], v[14:15], v[184:185] op_sel_hi:[1,0]
	v_pk_mul_f32 v[4:5], v[4:5], v[184:185] op_sel_hi:[1,0]
	v_pk_mul_f32 v[6:7], v[6:7], v[184:185] op_sel_hi:[1,0]
	v_pk_mul_f32 v[8:9], v[8:9], v[184:185] op_sel_hi:[1,0]
	v_pk_mul_f32 v[10:11], v[10:11], v[184:185] op_sel_hi:[1,0]
	v_pk_mul_f32 v[0:1], v[0:1], v[184:185] op_sel_hi:[1,0]
	v_pk_mul_f32 v[2:3], v[2:3], v[184:185] op_sel_hi:[1,0]
	v_pk_mul_f32 v[132:133], v[12:13], s[2:3]
	v_pk_mul_f32 v[134:135], v[14:15], s[2:3]
	v_pk_mul_f32 v[136:137], v[4:5], s[2:3]
	v_pk_mul_f32 v[138:139], v[6:7], s[2:3]
	v_exp_f32_e32 v132, v132
	v_exp_f32_e32 v133, v133
	v_exp_f32_e32 v134, v134
	v_exp_f32_e32 v135, v135
	v_exp_f32_e32 v136, v136
	v_exp_f32_e32 v137, v137
	v_exp_f32_e32 v138, v138
	v_exp_f32_e32 v139, v139
	v_pk_add_f32 v[132:133], v[132:133], s[100:101]
	v_pk_add_f32 v[134:135], v[134:135], s[100:101]
	v_pk_add_f32 v[136:137], v[136:137], s[100:101]
	v_pk_add_f32 v[138:139], v[138:139], s[100:101]
	v_rcp_f32_e32 v132, v132
	v_rcp_f32_e32 v133, v133
	v_rcp_f32_e32 v134, v134
	v_rcp_f32_e32 v135, v135
	v_rcp_f32_e32 v136, v136
	v_rcp_f32_e32 v137, v137
	v_rcp_f32_e32 v138, v138
	v_rcp_f32_e32 v139, v139
	v_pk_mul_f32 v[12:13], v[12:13], v[132:133]
	v_pk_mul_f32 v[14:15], v[14:15], v[134:135]
	v_pk_mul_f32 v[4:5], v[4:5], v[136:137]
	v_pk_mul_f32 v[6:7], v[6:7], v[138:139]
	v_pk_mul_f32 v[12:13], v[12:13], v[8:9]
	v_pk_mul_f32 v[14:15], v[14:15], v[10:11]
	v_pk_mul_f32 v[4:5], v[4:5], v[0:1]
	v_pk_mul_f32 v[6:7], v[6:7], v[2:3]
	v_cvt_pk_bf16_f32 v186, v12, v13
	v_cvt_pk_bf16_f32 v187, v14, v15
	v_cvt_pk_bf16_f32 v188, v4, v5
	v_cvt_pk_bf16_f32 v189, v6, v7
	global_store_dwordx4 v[182:183], v[186:189], off offset:2048
	s_mov_b64 s[0:1], -1
	s_andn2_b64 vcc, exec, s[4:5]
	s_cbranch_vccnz .LBB0_1127
	s_andn2_b64 vcc, exec, s[6:7]
	s_cbranch_vccnz .LBB0_1126
	s_barrier
	s_branch .LBB0_1126
